# prologue/final-norm row loops: all loads of a row in flight (counted waits), final-norm gain hoisted; EpiRes epilogue: wait moved below all 16 residual loads
# speedup vs baseline: 1.0047x; 1.0047x over previous
; __device__ __forceinline__ unsigned cvtpk(float lo, float hi) { f32x2_t v = {lo, hi}; bf16x2_t b = __builtin_convertvector(v, bf16x2_t); return __builtin_bit_cast(unsigned, b); }
; __global__ void __launch_bounds__(512, 2) fwd_kernel(Args a) {
;     ...
;     for (int row = gw; row < MROWS; row += ngw) {
;         const int b = row / LT, t = row - b * LT;
;         const float* src = t < NMETA ? a.meta + (size_t)t * DM : a.x + ((size_t)b * SEQ + (t - NMETA)) * DM;
;         bf16_t* hb = HB + (size_t)row * DM; float q = 0.f;
; #pragma unroll
;         for (int j = 0; j < 4; ++j) { const f32x4 v = *(const f32x4*)(src + j * 256 + lane * 4);
;             q += (v[0] * v[0] + v[1] * v[1]) + (v[2] * v[2] + v[3] * v[3]); u32x2 wv; wv.x = cvtpk(v[0], v[1]); wv.y = cvtpk(v[2], v[3]); *(u32x2*)(hb + j * 256 + lane * 4) = wv; }
; #pragma unroll
;         for (int s = 1; s < 64; s <<= 1) q += __shfl_xor(q, s);
;         if (lane < 16) SS[(size_t)row * 16 + lane] = lane == 0 ? q : 0.f;
.LBB0_12:
	s_lshl_b64 s[14:15], s[20:21], 12
	s_add_u32 s14, s16, s14
	s_addc_u32 s15, s17, s15
	s_waitcnt lgkmcnt(0)
	global_load_dwordx4 v[14:17], v12, s[14:15]
	global_load_dwordx4 v[18:21], v12, s[14:15] offset:1024
	global_load_dwordx4 v[22:25], v12, s[14:15] offset:2048
	global_load_dwordx4 v[26:29], v12, s[14:15] offset:3072
	v_lshl_add_u64 v[32:33], s[54:55], 0, v[4:5]
	v_add_co_u32_e32 v30, vcc, s7, v32
	s_nop 1
	v_addc_co_u32_e32 v31, vcc, 0, v33, vcc
	s_waitcnt vmcnt(3)
	v_cvt_pk_bf16_f32 v32, v14, v15
	v_cvt_pk_bf16_f32 v33, v16, v17
	global_store_dwordx2 v[30:31], v[32:33], off
	v_mul_f32_e32 v13, v15, v15
	v_mul_f32_e32 v15, v17, v17
	v_fmac_f32_e32 v13, v14, v14
	v_fmac_f32_e32 v15, v16, v16
	v_add_f32_e32 v13, v13, v15
	s_waitcnt vmcnt(3)
	v_cvt_pk_bf16_f32 v34, v18, v19
	v_cvt_pk_bf16_f32 v35, v20, v21
	global_store_dwordx2 v[30:31], v[34:35], off offset:512
	v_mul_f32_e32 v14, v19, v19
	v_mul_f32_e32 v15, v21, v21
	v_fmac_f32_e32 v14, v18, v18
	v_fmac_f32_e32 v15, v20, v20
	v_add_f32_e32 v14, v14, v15
	v_add_f32_e32 v13, v13, v14
	s_waitcnt vmcnt(3)
	v_cvt_pk_bf16_f32 v36, v22, v23
	v_cvt_pk_bf16_f32 v37, v24, v25
	global_store_dwordx2 v[30:31], v[36:37], off offset:1024
	v_mul_f32_e32 v14, v23, v23
	v_mul_f32_e32 v15, v25, v25
	v_fmac_f32_e32 v14, v22, v22
	v_fmac_f32_e32 v15, v24, v24
	v_add_f32_e32 v14, v14, v15
	v_add_f32_e32 v13, v13, v14
	s_waitcnt vmcnt(3)
	v_mul_f32_e32 v14, v27, v27
	v_mul_f32_e32 v15, v29, v29
	v_fmac_f32_e32 v14, v26, v26
	v_fmac_f32_e32 v15, v28, v28
	v_add_f32_e32 v14, v14, v15
	v_add_f32_e32 v13, v13, v14
	ds_bpermute_b32 v14, v1, v13
	v_cvt_pk_bf16_f32 v16, v26, v27
	v_cvt_pk_bf16_f32 v17, v28, v29
	global_store_dwordx2 v[30:31], v[16:17], off offset:1536
	s_waitcnt lgkmcnt(0)
	v_add_f32_e32 v13, v13, v14
	ds_bpermute_b32 v14, v7, v13
	s_waitcnt lgkmcnt(0)
	v_add_f32_e32 v13, v13, v14
	ds_bpermute_b32 v14, v8, v13
	s_waitcnt lgkmcnt(0)
	v_add_f32_e32 v13, v13, v14
	ds_bpermute_b32 v14, v9, v13
	s_waitcnt lgkmcnt(0)
	v_add_f32_e32 v13, v13, v14
	ds_bpermute_b32 v14, v10, v13
	s_waitcnt lgkmcnt(0)
	v_add_f32_e32 v13, v13, v14
	ds_bpermute_b32 v14, v11, v13
	s_and_saveexec_b64 s[14:15], s[0:1]
	s_cbranch_execz .LBB0_7
	s_waitcnt lgkmcnt(0)
	v_add_f32_e32 v13, v13, v14
	v_lshl_add_u64 v[14:15], s[54:55], 0, v[2:3]
	v_cndmask_b32_e64 v13, 0, v13, s[4:5]
	global_store_dword v[14:15], v13, off
	s_branch .LBB0_7

; __device__ __forceinline__ unsigned cvtpk(float lo, float hi) { f32x2_t v = {lo, hi}; bf16x2_t b = __builtin_convertvector(v, bf16x2_t); return __builtin_bit_cast(unsigned, b); }
; __device__ __forceinline__ float bflo(unsigned u) { return __uint_as_float(u << 16); }
; __device__ __forceinline__ float bfhi(unsigned u) { return __uint_as_float(u & 0xffff0000u); }
;     __device__ __forceinline__ void operator()(const AccT& acc, const Unit& u, int wr, int wc, int fr, int fq) const {
;     ...
;         bf16_t* bp0 = hb + (size_t)row0 * DM + col0;
;         u32x4 hv[2][4][2];
; #pragma unroll
;         for (int ai = 0; ai < 2; ++ai)
; #pragma unroll
;             for (int m = 0; m < 4; ++m)
; #pragma unroll
;                 for (int bj = 0; bj < 2; ++bj) hv[ai][m][bj] = *(const u32x4*)(bp0 + (size_t)(ai * 128 + m * 16) * DM + bj * 128);
; #pragma unroll
;         for (int ai = 0; ai < 2; ++ai)
; #pragma unroll
;             for (int m = 0; m < 4; ++m) { const int row = row0 + ai * 128 + m * 16; bf16_t* bp = bp0 + (size_t)(ai * 128 + m * 16) * DM; float q = 0.f;
; #pragma unroll
;                 for (int bj = 0; bj < 2; ++bj) { const u32x4 h4 = hv[ai][m][bj];
;                     f32x4 v0 = {bflo(h4.x), bfhi(h4.x), bflo(h4.y), bfhi(h4.y)}, v1 = {bflo(h4.z), bfhi(h4.z), bflo(h4.w), bfhi(h4.w)};
;                     v0 = v0 + acc[ai][bj][m][0] * c; v1 = v1 + acc[ai][bj][m][1] * c;
;                     q += ((v0[0] * v0[0] + v0[1] * v0[1]) + (v0[2] * v0[2] + v0[3] * v0[3])) + ((v1[0] * v1[0] + v1[1] * v1[1]) + (v1[2] * v1[2] + v1[3] * v1[3]));
;                     u32x4 w; w.x = cvtpk(v0[0], v0[1]); w.y = cvtpk(v0[2], v0[3]); w.z = cvtpk(v1[0], v1[1]); w.w = cvtpk(v1[2], v1[3]); *(u32x4*)(bp + bj * 128) = w; }
;                 q = xsum_16_32(q);
;                 if (fq == 0) ssn[(size_t)row * 16 + u.pn * 4 + wc] = q; }
.LBB0_300:
	v_lshl_add_u32 v206, s80, 8, v216
	v_ashrrev_i32_e32 v207, 31, v206
	v_lshl_or_b32 v2, s14, 8, v218
	v_lshlrev_b64 v[4:5], 11, v[206:207]
	v_lshl_add_u64 v[4:5], s[52:53], 0, v[4:5]
	v_ashrrev_i32_e32 v3, 31, v2
	v_lshl_add_u64 v[152:153], v[2:3], 1, v[4:5]
	global_load_dwordx4 v[220:223], v[152:153], off
	global_load_dwordx4 v[58:61], v[152:153], off offset:256
	v_add_co_u32_e32 v2, vcc, 0x8000, v152
	s_mov_b32 s0, 0x18000
	s_nop 0
	v_addc_co_u32_e32 v3, vcc, 0, v153, vcc
	global_load_dwordx4 v[54:57], v[2:3], off
	global_load_dwordx4 v[50:53], v[2:3], off offset:256
	v_add_co_u32_e32 v2, vcc, s96, v152
	s_nop 0
	s_nop 0
	v_addc_co_u32_e32 v3, vcc, 0, v153, vcc
	global_load_dwordx4 v[46:49], v[2:3], off
	global_load_dwordx4 v[42:45], v[2:3], off offset:256
	v_add_co_u32_e32 v2, vcc, s0, v152
	s_mov_b32 s0, 0x40000
	s_nop 0
	v_addc_co_u32_e32 v3, vcc, 0, v153, vcc
	global_load_dwordx4 v[38:41], v[2:3], off
	global_load_dwordx4 v[34:37], v[2:3], off offset:256
	v_add_co_u32_e32 v2, vcc, s0, v152
	s_mov_b32 s0, 0x48000
	s_nop 0
	v_addc_co_u32_e32 v3, vcc, 0, v153, vcc
	global_load_dwordx4 v[30:33], v[2:3], off
	global_load_dwordx4 v[26:29], v[2:3], off offset:256
	v_add_co_u32_e32 v2, vcc, s0, v152
	s_mov_b32 s0, 0x50000
	s_nop 0
	v_addc_co_u32_e32 v3, vcc, 0, v153, vcc
	global_load_dwordx4 v[22:25], v[2:3], off
	global_load_dwordx4 v[18:21], v[2:3], off offset:256
	v_add_co_u32_e32 v2, vcc, s0, v152
	s_mov_b32 s0, 0x58000
	s_nop 0
	v_addc_co_u32_e32 v3, vcc, 0, v153, vcc
	global_load_dwordx4 v[14:17], v[2:3], off
	global_load_dwordx4 v[10:13], v[2:3], off offset:256
	v_add_co_u32_e32 v2, vcc, s0, v152
	s_nop 0
	s_nop 0
	v_addc_co_u32_e32 v3, vcc, 0, v153, vcc
	global_load_dwordx4 v[6:9], v[2:3], off
	s_nop 0
	global_load_dwordx4 v[2:5], v[2:3], off offset:256
	s_waitcnt vmcnt(0)
	v_lshlrev_b32_e32 v224, 16, v220
	v_and_b32_e32 v225, 0xffff0000, v220
	v_lshlrev_b32_e32 v220, 16, v221
	v_and_b32_e32 v221, 0xffff0000, v221
	v_pk_add_f32 v[220:221], v[208:209], v[220:221]
	v_pk_add_f32 v[208:209], v[210:211], v[224:225]
	v_lshlrev_b32_e32 v226, 16, v222
	v_and_b32_e32 v227, 0xffff0000, v222
	v_mul_f32_e32 v202, v209, v209
	v_mul_f32_e32 v203, v221, v221
	v_lshlrev_b32_e32 v222, 16, v223
	v_and_b32_e32 v223, 0xffff0000, v223
	v_pk_add_f32 v[210:211], v[214:215], v[226:227]
	v_fmac_f32_e32 v202, v208, v208
	v_fmac_f32_e32 v203, v220, v220
	v_pk_add_f32 v[212:213], v[212:213], v[222:223]
	v_add_f32_e32 v202, v202, v203
	v_mul_f32_e32 v203, v211, v211
	v_fmac_f32_e32 v203, v210, v210
	v_cvt_pk_bf16_f32 v208, v208, v209
	v_cvt_pk_bf16_f32 v209, v220, v221
	v_cvt_pk_bf16_f32 v210, v210, v211
	v_cvt_pk_bf16_f32 v211, v212, v213
	global_store_dwordx4 v[152:153], v[208:211], off
	v_mul_f32_e32 v214, v213, v213
	v_fmac_f32_e32 v214, v212, v212
	v_lshlrev_b32_e32 v208, 16, v58
	v_and_b32_e32 v209, 0xffff0000, v58
	v_lshlrev_b32_e32 v58, 16, v59
	v_and_b32_e32 v59, 0xffff0000, v59
	v_lshlrev_b32_e32 v210, 16, v60
	v_and_b32_e32 v211, 0xffff0000, v60
	v_lshlrev_b32_e32 v60, 16, v61
	v_and_b32_e32 v61, 0xffff0000, v61
	v_pk_add_f32 v[192:193], v[192:193], v[58:59]
	v_pk_add_f32 v[58:59], v[190:191], v[208:209]
	v_pk_add_f32 v[188:189], v[188:189], v[60:61]
	v_pk_add_f32 v[60:61], v[186:187], v[210:211]
	v_mul_f32_e32 v186, v59, v59
	v_mul_f32_e32 v187, v193, v193
	v_fmac_f32_e32 v186, v58, v58
	v_fmac_f32_e32 v187, v192, v192
	v_add_f32_e32 v186, v186, v187
	v_mul_f32_e32 v187, v61, v61
	v_mul_f32_e32 v190, v189, v189
	v_fmac_f32_e32 v187, v60, v60
	v_fmac_f32_e32 v190, v188, v188
	v_add_f32_e32 v203, v203, v214
	v_add_f32_e32 v187, v187, v190
	v_add_f32_e32 v202, v202, v203
	v_add_f32_e32 v186, v186, v187
	v_add_f32_e32 v186, v202, v186
	v_cvt_pk_bf16_f32 v58, v58, v59
	v_cvt_pk_bf16_f32 v59, v192, v193
	v_cvt_pk_bf16_f32 v60, v60, v61
	v_cvt_pk_bf16_f32 v61, v188, v189
	global_store_dwordx4 v[152:153], v[58:61], off offset:256
	s_lshl_b32 s0, s14, 2
	s_ashr_i32 s1, s0, 31
	v_mov_b32_e32 v58, v186
	s_nop 1
	v_permlane16_swap_b32_e32 v186, v58
	v_add_f32_e32 v60, v186, v58
	v_mov_b32_e32 v61, v60
	v_lshlrev_b64 v[58:59], 6, v[206:207]
	s_nop 0
	v_permlane32_swap_b32_e32 v60, v61
	v_lshl_add_u64 v[58:59], s[22:23], 0, v[58:59]
	s_and_saveexec_b64 s[28:29], s[40:41]
	s_cbranch_execz .LBB0_302
	v_lshl_add_u64 v[186:187], s[0:1], 2, v[58:59]
	s_lshl_b32 s80, s30, 2
	v_lshl_add_u64 v[186:187], v[186:187], 0, s[80:81]
	v_add_f32_e32 v60, v60, v61
	global_store_dword v[186:187], v60, off

; __device__ __forceinline__ unsigned cvtpk(float lo, float hi) { f32x2_t v = {lo, hi}; bf16x2_t b = __builtin_convertvector(v, bf16x2_t); return __builtin_bit_cast(unsigned, b); }
; __device__ __forceinline__ float bflo(unsigned u) { return __uint_as_float(u << 16); }
; __device__ __forceinline__ float bfhi(unsigned u) { return __uint_as_float(u & 0xffff0000u); }
;     __device__ __forceinline__ void operator()(const AccT& acc, const Unit& u, int wr, int wc, int fr, int fq) const {
;     ...
;         bf16_t* bp0 = hb + (size_t)row0 * DM + col0;
;         u32x4 hv[2][4][2];
; #pragma unroll
;         for (int ai = 0; ai < 2; ++ai)
; #pragma unroll
;             for (int m = 0; m < 4; ++m)
; #pragma unroll
;                 for (int bj = 0; bj < 2; ++bj) hv[ai][m][bj] = *(const u32x4*)(bp0 + (size_t)(ai * 128 + m * 16) * DM + bj * 128);
; #pragma unroll
;         for (int ai = 0; ai < 2; ++ai)
; #pragma unroll
;             for (int m = 0; m < 4; ++m) { const int row = row0 + ai * 128 + m * 16; bf16_t* bp = bp0 + (size_t)(ai * 128 + m * 16) * DM; float q = 0.f;
; #pragma unroll
;                 for (int bj = 0; bj < 2; ++bj) { const u32x4 h4 = hv[ai][m][bj];
;                     f32x4 v0 = {bflo(h4.x), bfhi(h4.x), bflo(h4.y), bfhi(h4.y)}, v1 = {bflo(h4.z), bfhi(h4.z), bflo(h4.w), bfhi(h4.w)};
;                     v0 = v0 + acc[ai][bj][m][0] * c; v1 = v1 + acc[ai][bj][m][1] * c;
;                     q += ((v0[0] * v0[0] + v0[1] * v0[1]) + (v0[2] * v0[2] + v0[3] * v0[3])) + ((v1[0] * v1[0] + v1[1] * v1[1]) + (v1[2] * v1[2] + v1[3] * v1[3]));
;                     u32x4 w; w.x = cvtpk(v0[0], v0[1]); w.y = cvtpk(v0[2], v0[3]); w.z = cvtpk(v1[0], v1[1]); w.w = cvtpk(v1[2], v1[3]); *(u32x4*)(bp + bj * 128) = w; }
;                 q = xsum_16_32(q);
;                 if (fq == 0) ssn[(size_t)row * 16 + u.pn * 4 + wc] = q; }
.LBB0_1780:
	v_lshl_add_u32 v214, s80, 8, v216
	v_ashrrev_i32_e32 v215, 31, v214
	v_lshl_or_b32 v130, s14, 8, v218
	v_lshlrev_b64 v[132:133], 11, v[214:215]
	v_lshl_add_u64 v[132:133], s[52:53], 0, v[132:133]
	v_ashrrev_i32_e32 v131, 31, v130
	v_lshl_add_u64 v[212:213], v[130:131], 1, v[132:133]
	global_load_dwordx4 v[220:223], v[212:213], off
	global_load_dwordx4 v[186:189], v[212:213], off offset:256
	v_add_co_u32_e32 v130, vcc, 0x8000, v212
	s_mov_b32 s0, 0x18000
	s_nop 0
	v_addc_co_u32_e32 v131, vcc, 0, v213, vcc
	global_load_dwordx4 v[182:185], v[130:131], off
	global_load_dwordx4 v[178:181], v[130:131], off offset:256
	v_add_co_u32_e32 v130, vcc, s54, v212
	s_nop 0
	s_nop 0
	v_addc_co_u32_e32 v131, vcc, 0, v213, vcc
	global_load_dwordx4 v[174:177], v[130:131], off
	global_load_dwordx4 v[170:173], v[130:131], off offset:256
	v_add_co_u32_e32 v130, vcc, s0, v212
	s_mov_b32 s0, 0x40000
	s_nop 0
	v_addc_co_u32_e32 v131, vcc, 0, v213, vcc
	global_load_dwordx4 v[166:169], v[130:131], off
	global_load_dwordx4 v[162:165], v[130:131], off offset:256
	v_add_co_u32_e32 v130, vcc, s0, v212
	s_mov_b32 s0, 0x48000
	s_nop 0
	v_addc_co_u32_e32 v131, vcc, 0, v213, vcc
	global_load_dwordx4 v[158:161], v[130:131], off
	global_load_dwordx4 v[154:157], v[130:131], off offset:256
	v_add_co_u32_e32 v130, vcc, s0, v212
	s_mov_b32 s0, 0x50000
	s_nop 0
	v_addc_co_u32_e32 v131, vcc, 0, v213, vcc
	global_load_dwordx4 v[150:153], v[130:131], off
	global_load_dwordx4 v[146:149], v[130:131], off offset:256
	v_add_co_u32_e32 v130, vcc, s0, v212
	s_mov_b32 s0, 0x58000
	s_nop 0
	v_addc_co_u32_e32 v131, vcc, 0, v213, vcc
	global_load_dwordx4 v[142:145], v[130:131], off
	global_load_dwordx4 v[138:141], v[130:131], off offset:256
	v_add_co_u32_e32 v130, vcc, s0, v212
	s_nop 0
	s_nop 0
	v_addc_co_u32_e32 v131, vcc, 0, v213, vcc
	global_load_dwordx4 v[134:137], v[130:131], off
	s_nop 0
	global_load_dwordx4 v[130:133], v[130:131], off offset:256
	s_waitcnt vmcnt(0)
	v_lshlrev_b32_e32 v202, 16, v220
	v_and_b32_e32 v203, 0xffff0000, v220
	v_lshlrev_b32_e32 v220, 16, v221
	v_and_b32_e32 v221, 0xffff0000, v221
	v_lshlrev_b32_e32 v224, 16, v222
	v_and_b32_e32 v225, 0xffff0000, v222
	v_lshlrev_b32_e32 v222, 16, v223
	v_and_b32_e32 v223, 0xffff0000, v223
	v_pk_add_f32 v[124:125], v[124:125], v[220:221]
	v_pk_add_f32 v[122:123], v[122:123], v[202:203]
	v_pk_add_f32 v[128:129], v[128:129], v[222:223]
	v_pk_add_f32 v[126:127], v[126:127], v[224:225]
	v_mul_f32_e32 v202, v123, v123
	v_mul_f32_e32 v203, v125, v125
	v_fmac_f32_e32 v202, v122, v122
	v_fmac_f32_e32 v203, v124, v124
	v_cvt_pk_bf16_f32 v122, v122, v123
	v_cvt_pk_bf16_f32 v123, v124, v125
	v_cvt_pk_bf16_f32 v124, v126, v127
	v_cvt_pk_bf16_f32 v125, v128, v129
	v_add_f32_e32 v202, v202, v203
	v_mul_f32_e32 v203, v127, v127
	v_mul_f32_e32 v220, v129, v129
	global_store_dwordx4 v[212:213], v[122:125], off
	v_fmac_f32_e32 v203, v126, v126
	v_fmac_f32_e32 v220, v128, v128
	v_lshlrev_b32_e32 v122, 16, v186
	v_and_b32_e32 v123, 0xffff0000, v186
	v_lshlrev_b32_e32 v124, 16, v187
	v_and_b32_e32 v125, 0xffff0000, v187
	v_lshlrev_b32_e32 v126, 16, v188
	v_and_b32_e32 v127, 0xffff0000, v188
	v_lshlrev_b32_e32 v128, 16, v189
	v_and_b32_e32 v129, 0xffff0000, v189
	v_pk_add_f32 v[120:121], v[120:121], v[124:125]
	v_pk_add_f32 v[118:119], v[118:119], v[122:123]
	v_pk_add_f32 v[122:123], v[116:117], v[128:129]
	v_pk_add_f32 v[116:117], v[114:115], v[126:127]
	v_mul_f32_e32 v114, v119, v119
	v_mul_f32_e32 v115, v121, v121
	v_fmac_f32_e32 v114, v118, v118
	v_fmac_f32_e32 v115, v120, v120
	v_add_f32_e32 v114, v114, v115
	v_mul_f32_e32 v115, v117, v117
	v_mul_f32_e32 v124, v123, v123
	v_fmac_f32_e32 v115, v116, v116
	v_fmac_f32_e32 v124, v122, v122
	v_add_f32_e32 v203, v203, v220
	v_add_f32_e32 v115, v115, v124
	v_add_f32_e32 v202, v202, v203
	v_add_f32_e32 v114, v114, v115
	v_add_f32_e32 v124, v202, v114
	v_cvt_pk_bf16_f32 v114, v118, v119
	v_cvt_pk_bf16_f32 v115, v120, v121
	v_cvt_pk_bf16_f32 v116, v116, v117
	v_cvt_pk_bf16_f32 v117, v122, v123
	global_store_dwordx4 v[212:213], v[114:117], off offset:256
	s_lshl_b32 s0, s14, 2
	v_readlane_b32 s14, v255, 48
	v_mov_b32_e32 v114, v124
	s_nop 1
	v_permlane16_swap_b32_e32 v124, v114
	v_add_f32_e32 v116, v124, v114
	v_mov_b32_e32 v117, v116
	v_lshlrev_b64 v[114:115], 6, v[214:215]
	v_readlane_b32 s15, v255, 49
	s_ashr_i32 s1, s0, 31
	v_permlane32_swap_b32_e32 v116, v117
	v_lshl_add_u64 v[114:115], s[14:15], 0, v[114:115]
	s_and_saveexec_b64 s[28:29], s[44:45]
	s_cbranch_execz .LBB0_1782
	v_lshl_add_u64 v[118:119], s[0:1], 2, v[114:115]
	s_lshl_b32 s80, s30, 2
	v_lshl_add_u64 v[118:119], v[118:119], 0, s[80:81]
	v_add_f32_e32 v116, v116, v117
	global_store_dword v[118:119], v116, off

; __device__ __forceinline__ unsigned cvtpk(float lo, float hi) { f32x2_t v = {lo, hi}; bf16x2_t b = __builtin_convertvector(v, bf16x2_t); return __builtin_bit_cast(unsigned, b); }
; __device__ __forceinline__ float bflo(unsigned u) { return __uint_as_float(u << 16); }
; __device__ __forceinline__ float bfhi(unsigned u) { return __uint_as_float(u & 0xffff0000u); }
;     __device__ __forceinline__ void operator()(const AccT& acc, const Unit& u, int wr, int wc, int fr, int fq) const {
;     ...
;         bf16_t* bp0 = hb + (size_t)row0 * DM + col0;
;         u32x4 hv[2][4][2];
; #pragma unroll
;         for (int ai = 0; ai < 2; ++ai)
; #pragma unroll
;             for (int m = 0; m < 4; ++m)
; #pragma unroll
;                 for (int bj = 0; bj < 2; ++bj) hv[ai][m][bj] = *(const u32x4*)(bp0 + (size_t)(ai * 128 + m * 16) * DM + bj * 128);
; #pragma unroll
;         for (int ai = 0; ai < 2; ++ai)
; #pragma unroll
;             for (int m = 0; m < 4; ++m) { const int row = row0 + ai * 128 + m * 16; bf16_t* bp = bp0 + (size_t)(ai * 128 + m * 16) * DM; float q = 0.f;
; #pragma unroll
;                 for (int bj = 0; bj < 2; ++bj) { const u32x4 h4 = hv[ai][m][bj];
;                     f32x4 v0 = {bflo(h4.x), bfhi(h4.x), bflo(h4.y), bfhi(h4.y)}, v1 = {bflo(h4.z), bfhi(h4.z), bflo(h4.w), bfhi(h4.w)};
;                     v0 = v0 + acc[ai][bj][m][0] * c; v1 = v1 + acc[ai][bj][m][1] * c;
;                     q += ((v0[0] * v0[0] + v0[1] * v0[1]) + (v0[2] * v0[2] + v0[3] * v0[3])) + ((v1[0] * v1[0] + v1[1] * v1[1]) + (v1[2] * v1[2] + v1[3] * v1[3]));
;                     u32x4 w; w.x = cvtpk(v0[0], v0[1]); w.y = cvtpk(v0[2], v0[3]); w.z = cvtpk(v1[0], v1[1]); w.w = cvtpk(v1[2], v1[3]); *(u32x4*)(bp + bj * 128) = w; }
;                 q = xsum_16_32(q);
;                 if (fq == 0) ssn[(size_t)row * 16 + u.pn * 4 + wc] = q; }
.LBB0_2030:
	v_lshl_add_u32 v206, s80, 8, v216
	v_ashrrev_i32_e32 v207, 31, v206
	v_readlane_b32 s0, v252, 21
	v_lshl_or_b32 v2, s14, 8, v218
	v_lshlrev_b64 v[4:5], 11, v[206:207]
	v_readlane_b32 s1, v252, 22
	v_ashrrev_i32_e32 v3, 31, v2
	s_nop 0
	v_lshl_add_u64 v[4:5], s[0:1], 0, v[4:5]
	v_lshl_add_u64 v[152:153], v[2:3], 1, v[4:5]
	global_load_dwordx4 v[220:223], v[152:153], off
	global_load_dwordx4 v[58:61], v[152:153], off offset:256
	v_add_co_u32_e32 v2, vcc, 0x8000, v152
	s_mov_b32 s0, 0x18000
	s_nop 0
	v_addc_co_u32_e32 v3, vcc, 0, v153, vcc
	global_load_dwordx4 v[54:57], v[2:3], off
	global_load_dwordx4 v[50:53], v[2:3], off offset:256
	v_add_co_u32_e32 v2, vcc, s54, v152
	s_nop 0
	s_nop 0
	v_addc_co_u32_e32 v3, vcc, 0, v153, vcc
	global_load_dwordx4 v[46:49], v[2:3], off
	global_load_dwordx4 v[42:45], v[2:3], off offset:256
	v_add_co_u32_e32 v2, vcc, s0, v152
	s_mov_b32 s0, 0x40000
	s_nop 0
	v_addc_co_u32_e32 v3, vcc, 0, v153, vcc
	global_load_dwordx4 v[38:41], v[2:3], off
	global_load_dwordx4 v[34:37], v[2:3], off offset:256
	v_add_co_u32_e32 v2, vcc, s0, v152
	s_mov_b32 s0, 0x48000
	s_nop 0
	v_addc_co_u32_e32 v3, vcc, 0, v153, vcc
	global_load_dwordx4 v[30:33], v[2:3], off
	global_load_dwordx4 v[26:29], v[2:3], off offset:256
	v_add_co_u32_e32 v2, vcc, s0, v152
	s_mov_b32 s0, 0x50000
	s_nop 0
	v_addc_co_u32_e32 v3, vcc, 0, v153, vcc
	global_load_dwordx4 v[22:25], v[2:3], off
	global_load_dwordx4 v[18:21], v[2:3], off offset:256
	v_add_co_u32_e32 v2, vcc, s0, v152
	s_mov_b32 s0, 0x58000
	s_nop 0
	v_addc_co_u32_e32 v3, vcc, 0, v153, vcc
	global_load_dwordx4 v[14:17], v[2:3], off
	global_load_dwordx4 v[10:13], v[2:3], off offset:256
	v_add_co_u32_e32 v2, vcc, s0, v152
	s_nop 0
	s_nop 0
	v_addc_co_u32_e32 v3, vcc, 0, v153, vcc
	global_load_dwordx4 v[6:9], v[2:3], off
	s_nop 0
	global_load_dwordx4 v[2:5], v[2:3], off offset:256
	s_waitcnt vmcnt(0)
	v_lshlrev_b32_e32 v202, 16, v220
	v_and_b32_e32 v203, 0xffff0000, v220
	v_lshlrev_b32_e32 v220, 16, v221
	v_and_b32_e32 v221, 0xffff0000, v221
	v_pk_add_f32 v[220:221], v[208:209], v[220:221]
	v_pk_add_f32 v[202:203], v[210:211], v[202:203]
	v_lshlrev_b32_e32 v224, 16, v222
	v_and_b32_e32 v225, 0xffff0000, v222
	v_lshlrev_b32_e32 v222, 16, v223
	v_and_b32_e32 v223, 0xffff0000, v223
	v_mul_f32_e32 v208, v203, v203
	v_mul_f32_e32 v209, v221, v221
	v_pk_add_f32 v[212:213], v[212:213], v[222:223]
	v_pk_add_f32 v[210:211], v[214:215], v[224:225]
	v_fmac_f32_e32 v208, v202, v202
	v_fmac_f32_e32 v209, v220, v220
	v_add_f32_e32 v208, v208, v209
	v_mul_f32_e32 v209, v211, v211
	v_mul_f32_e32 v214, v213, v213
	v_fmac_f32_e32 v209, v210, v210
	v_fmac_f32_e32 v214, v212, v212
	v_add_f32_e32 v209, v209, v214
	v_add_f32_e32 v214, v208, v209
	v_cvt_pk_bf16_f32 v208, v202, v203
	v_cvt_pk_bf16_f32 v209, v220, v221
	v_cvt_pk_bf16_f32 v210, v210, v211
	v_cvt_pk_bf16_f32 v211, v212, v213
	v_lshlrev_b32_e32 v202, 16, v58
	v_and_b32_e32 v203, 0xffff0000, v58
	v_lshlrev_b32_e32 v58, 16, v59
	v_and_b32_e32 v59, 0xffff0000, v59
	global_store_dwordx4 v[152:153], v[208:211], off
	v_pk_add_f32 v[192:193], v[192:193], v[58:59]
	v_pk_add_f32 v[58:59], v[190:191], v[202:203]
	v_lshlrev_b32_e32 v208, 16, v60
	v_and_b32_e32 v209, 0xffff0000, v60
	v_lshlrev_b32_e32 v60, 16, v61
	v_and_b32_e32 v61, 0xffff0000, v61
	v_pk_add_f32 v[188:189], v[188:189], v[60:61]
	v_pk_add_f32 v[60:61], v[186:187], v[208:209]
	v_mul_f32_e32 v186, v59, v59
	v_mul_f32_e32 v187, v193, v193
	v_fmac_f32_e32 v186, v58, v58
	v_fmac_f32_e32 v187, v192, v192
	v_add_f32_e32 v186, v186, v187
	v_mul_f32_e32 v187, v61, v61
	v_mul_f32_e32 v190, v189, v189
	v_fmac_f32_e32 v187, v60, v60
	v_fmac_f32_e32 v190, v188, v188
	v_add_f32_e32 v187, v187, v190
	v_add_f32_e32 v186, v186, v187
	v_add_f32_e32 v186, v214, v186
	v_cvt_pk_bf16_f32 v58, v58, v59
	v_cvt_pk_bf16_f32 v59, v192, v193
	v_cvt_pk_bf16_f32 v60, v60, v61
	v_cvt_pk_bf16_f32 v61, v188, v189
	global_store_dwordx4 v[152:153], v[58:61], off offset:256
	s_lshl_b32 s0, s14, 2
	s_ashr_i32 s1, s0, 31
	v_mov_b32_e32 v58, v186
	s_nop 1
	v_permlane16_swap_b32_e32 v186, v58
	v_add_f32_e32 v60, v186, v58
	v_mov_b32_e32 v61, v60
	v_lshlrev_b64 v[58:59], 6, v[206:207]
	s_nop 0
	v_permlane32_swap_b32_e32 v60, v61
	v_lshl_add_u64 v[58:59], s[22:23], 0, v[58:59]
	s_and_saveexec_b64 s[28:29], s[38:39]
	s_cbranch_execz .LBB0_2032
	v_lshl_add_u64 v[186:187], s[0:1], 2, v[58:59]
	s_lshl_b32 s80, s30, 2
	v_lshl_add_u64 v[186:187], v[186:187], 0, s[80:81]
	v_add_f32_e32 v60, v60, v61
	global_store_dword v[186:187], v60, off

; __device__ __forceinline__ float bflo(unsigned u) { return __uint_as_float(u << 16); }
; __device__ __forceinline__ float bfhi(unsigned u) { return __uint_as_float(u & 0xffff0000u); }
; __global__ void __launch_bounds__(512, 2) fwd_kernel(Args a) {
;     ...
;     { const float* ssf = SS; int tid2 = threadIdx.x; asm volatile("" : "+v"(tid2)); const int lane = tid2 & 63, gw = blockIdx.x * 8 + __builtin_amdgcn_readfirstlane(tid2 >> 6);
;       for (int row = gw; row < NBATCH * SEQ; row += ngw) { const int b = row / SEQ, sq = row - b * SEQ, m = b * LT + NMETA + sq; const float rs = rstd_of(ssf, m);
;           const bf16_t* hp = HB + (size_t)m * DM; float* p = a.out + (size_t)row * DM;
; #pragma unroll
;           for (int j = 0; j < 4; ++j) { const u32x2 h2 = *(const u32x2*)(hp + j * 256 + lane * 4); const f32x4 gg = *(const f32x4*)(a.final_norm + j * 256 + lane * 4);
;               f32x4 v = {bflo(h2.x), bfhi(h2.x), bflo(h2.y), bfhi(h2.y)}; v = v * rs * gg; *(f32x4*)(p + j * 256 + lane * 4) = v; } } }
.LBB0_2143:
	v_readlane_b32 s1, v252, 20
	v_readfirstlane_b32 s0, v234
	s_ashr_i32 s0, s0, 6
	s_add_i32 s0, s0, s1
	v_readlane_b32 s4, v254, 46
	s_cmp_gt_i32 s0, 0xffff
	v_readlane_b32 s14, v254, 56
	v_readlane_b32 s15, v254, 57
	v_readlane_b32 s16, v254, 58
	v_readlane_b32 s17, v254, 59
	v_readlane_b32 s18, v254, 60
	v_readlane_b32 s19, v254, 61
	v_readlane_b32 s5, v254, 47
	v_readlane_b32 s6, v254, 48
	v_readlane_b32 s7, v254, 49
	v_readlane_b32 s8, v254, 50
	v_readlane_b32 s9, v254, 51
	v_readlane_b32 s10, v254, 52
	v_readlane_b32 s11, v254, 53
	v_readlane_b32 s12, v254, 54
	v_readlane_b32 s13, v254, 55
	s_cbranch_scc1 .LBB0_2146
	v_lshlrev_b32_e32 v0, 2, v234
	v_and_b32_e32 v4, 0xfc, v0
	v_lshlrev_b32_e32 v0, 1, v4
	v_mov_b32_e32 v1, 0
	s_ashr_i32 s1, s0, 31
	s_mov_b64 s[10:11], s[14:15]
	s_mov_b64 s[12:13], s[16:17]
	v_lshl_add_u64 v[2:3], s[52:53], 0, v[0:1]
	v_lshlrev_b32_e32 v0, 2, v4
	s_lshl_b64 s[2:3], s[0:1], 12
	v_lshl_add_u64 v[4:5], s[10:11], 0, v[0:1]
	v_and_b32_e32 v0, 63, v234
	s_add_u32 s2, s12, s2
	v_lshlrev_b32_e32 v0, 4, v0
	s_addc_u32 s3, s13, s3
	s_ashr_i32 s95, s94, 31
	s_mov_b64 s[14:15], s[18:19]
	v_lshl_add_u64 v[6:7], s[2:3], 0, v[0:1]
	s_lshl_b64 s[2:3], s[94:95], 12
	v_mov_b32_e32 v0, 0x358637bd
	s_mov_b32 s1, 0x800000
	global_load_dwordx4 v[40:43], v[4:5], off
	global_load_dwordx4 v[44:47], v[4:5], off offset:1024
	global_load_dwordx4 v[48:51], v[4:5], off offset:2048
	global_load_dwordx4 v[52:55], v[4:5], off offset:3072
.LBB0_2145:
	s_ashr_i32 s4, s0, 31
	s_lshr_b32 s4, s4, 20
	s_add_i32 s4, s0, s4
	s_ashr_i32 s4, s4, 12
	s_lshl_b32 s4, s4, 4
	s_add_i32 s4, s0, s4
	s_add_i32 s4, s4, 16
	s_ashr_i32 s5, s4, 31
	s_lshl_b64 s[6:7], s[4:5], 6
	s_add_u32 s6, s14, s6
	s_addc_u32 s7, s15, s7
	global_load_dwordx4 v[8:11], v1, s[6:7]
	global_load_dwordx4 v[12:15], v1, s[6:7] offset:16
	global_load_dwordx4 v[16:19], v1, s[6:7] offset:32
	global_load_dwordx4 v[20:23], v1, s[6:7] offset:48
	s_lshl_b64 s[4:5], s[4:5], 11
	v_lshl_add_u64 v[28:29], v[2:3], 0, s[4:5]
	global_load_dwordx2 v[30:31], v[28:29], off
	global_load_dwordx2 v[56:57], v[28:29], off offset:512
	global_load_dwordx2 v[58:59], v[28:29], off offset:1024
	global_load_dwordx2 v[60:61], v[28:29], off offset:1536
	s_add_i32 s0, s0, s94
	s_cmp_gt_i32 s0, 0xffff
	s_waitcnt vmcnt(0)
	v_mov_b32_e32 v32, v9
	v_mov_b32_e32 v33, v10
	v_mov_b32_e32 v9, v11
	v_mov_b32_e32 v10, v13
	v_mov_b32_e32 v11, v14
	v_mov_b32_e32 v13, v15
	v_pk_add_f32 v[8:9], v[32:33], v[8:9]
	v_pk_add_f32 v[10:11], v[10:11], v[12:13]
	v_pk_add_f32 v[8:9], v[8:9], v[8:9] op_sel:[0,1] op_sel_hi:[1,0]
	v_pk_add_f32 v[10:11], v[10:11], v[10:11] op_sel:[0,1] op_sel_hi:[1,0]
	v_add_f32_e32 v14, v16, v17
	v_add_f32_e32 v16, v18, v19
	v_mov_b32_e32 v15, v22
	v_mov_b32_e32 v17, v23
	v_mov_b32_e32 v9, v20
	v_mov_b32_e32 v11, v21
	v_pk_add_f32 v[12:13], v[14:15], v[16:17]
	v_pk_add_f32 v[8:9], v[8:9], v[10:11]
	v_lshlrev_b32_e32 v14, 16, v30
	v_pk_add_f32 v[8:9], v[8:9], v[12:13]
	v_and_b32_e32 v15, 0xffff0000, v30
	v_add_f32_e32 v8, v8, v9
	v_fmamk_f32 v8, v8, 0x3a800000, v0
	v_mul_f32_e32 v9, 0x4b800000, v8
	v_cmp_gt_f32_e32 vcc, s1, v8
	v_lshlrev_b32_e32 v16, 16, v31
	v_and_b32_e32 v17, 0xffff0000, v31
	v_cndmask_b32_e32 v8, v8, v9, vcc
	v_rsq_f32_e32 v8, v8
	s_nop 0
	v_mul_f32_e32 v9, 0x45800000, v8
	v_cndmask_b32_e32 v12, v8, v9, vcc
	v_pk_mul_f32 v[8:9], v[12:13], v[14:15] op_sel_hi:[0,1]
	v_pk_mul_f32 v[10:11], v[12:13], v[16:17] op_sel_hi:[0,1]
	v_pk_mul_f32 v[10:11], v[42:43], v[10:11]
	v_pk_mul_f32 v[8:9], v[40:41], v[8:9]
	global_store_dwordx4 v[6:7], v[8:11], off
	v_lshlrev_b32_e32 v16, 16, v56
	v_and_b32_e32 v17, 0xffff0000, v56
	v_lshlrev_b32_e32 v14, 16, v57
	v_and_b32_e32 v15, 0xffff0000, v57
	v_pk_mul_f32 v[16:17], v[12:13], v[16:17] op_sel_hi:[0,1]
	v_pk_mul_f32 v[14:15], v[12:13], v[14:15] op_sel_hi:[0,1]
	v_pk_mul_f32 v[10:11], v[46:47], v[14:15]
	v_pk_mul_f32 v[8:9], v[44:45], v[16:17]
	global_store_dwordx4 v[6:7], v[8:11], off offset:1024
	v_lshlrev_b32_e32 v16, 16, v58
	v_and_b32_e32 v17, 0xffff0000, v58
	v_lshlrev_b32_e32 v14, 16, v59
	v_and_b32_e32 v15, 0xffff0000, v59
	v_pk_mul_f32 v[16:17], v[12:13], v[16:17] op_sel_hi:[0,1]
	v_pk_mul_f32 v[14:15], v[12:13], v[14:15] op_sel_hi:[0,1]
	v_pk_mul_f32 v[10:11], v[50:51], v[14:15]
	v_pk_mul_f32 v[8:9], v[48:49], v[16:17]
	global_store_dwordx4 v[6:7], v[8:11], off offset:2048
	v_lshlrev_b32_e32 v16, 16, v60
	v_and_b32_e32 v17, 0xffff0000, v60
	v_lshlrev_b32_e32 v14, 16, v61
	v_and_b32_e32 v15, 0xffff0000, v61
	v_pk_mul_f32 v[16:17], v[12:13], v[16:17] op_sel_hi:[0,1]
	v_pk_mul_f32 v[14:15], v[12:13], v[14:15] op_sel_hi:[0,1]
	v_pk_mul_f32 v[10:11], v[54:55], v[14:15]
	v_pk_mul_f32 v[8:9], v[52:53], v[16:17]
	global_store_dwordx4 v[6:7], v[8:11], off offset:3072
	v_lshl_add_u64 v[6:7], v[6:7], 0, s[2:3]
	s_cbranch_scc0 .LBB0_2145
